# MLA loop: V-frag buffers reused as extra Qb buffers (2 Qb re-reads instead of 6)
# speedup vs baseline: 1.0335x; 1.0006x over previous
; #define ALAS __attribute__((address_space(3)))
; #define AMFMA(a, b, c) __builtin_amdgcn_mfma_f32_32x32x16_bf16((a), (b), (c), 0, 0, 0)
; template <bool SUB> __device__ __forceinline__ void attn_unit_r2b(const AU& u, ALAS unsigned char* lds, float mb2) {
;     ...
; #pragma unroll
;             for (int d0 = 0; d0 < 6; ++d0) {
;                 const bf16x8 k0 = *(const ALAS bf16x8*)(kb + d0 * 32), k1 = *(const ALAS bf16x8*)(kb + 32 * KP + d0 * 32); const bf16x8 qbv = *(const ALAS bf16x8*)(qbl + d0 * 1024);
;                 Sa0 = AMFMA(k0, qa[d0], Sa0); Sa1 = AMFMA(k1, qa[d0], Sa1); Sb0 = AMFMA(k0, qbv, Sb0); Sb1 = AMFMA(k1, qbv, Sb1);
;                 if (d0 & 1) __builtin_amdgcn_sched_barrier(0);
;             }
;     ...
;             R2B_SOFT(Sa0, Sa1, paa, la);
;             __builtin_amdgcn_sched_barrier(0);
;             R2B_SOFT(Sb0, Sb1, pab, lb);
.Lr2b_noload:
	s_and_b32 s58, s62, 1
	s_mul_i32 s34, s58, 0x3400
	v_add_u32_e32 v188, s34, v168
	ds_read_b128 v[218:221], v188 offset:0
	ds_read_b128 v[222:225], v188 offset:32
	ds_read_b128 v[226:229], v188 offset:64
	ds_read_b128 v[230:233], v188 offset:96
	ds_read_b128 v[234:237], v188 offset:128
	ds_read_b128 v[238:241], v188 offset:160
	ds_read_b128 v[176:179], v193 offset:45056
	ds_read_b128 v[180:183], v193 offset:46080
	ds_read_b128 v[184:187], v193 offset:47104
	ds_read_b128 v[248:251], v193 offset:48128
	ds_read_b128 v[244:247], v193 offset:49152
	s_mul_i32 s34, s58, 0x2400
	v_add_u32_e32 v189, s34, v197
	s_waitcnt lgkmcnt(10)
	v_mfma_f32_32x32x16_bf16 v[96:111], v[218:221], v[128:131], 0
	v_lshl_add_u64 v[166:167], v[166:167], 0, s[8:9]
	v_add_f32_e32 v242, v112, v242
	v_add_f32_e32 v243, v80, v243
	v_add_f32_e32 v242, v113, v242
	v_add_f32_e32 v243, v81, v243
	s_waitcnt lgkmcnt(9)
	v_mfma_f32_32x32x16_bf16 v[96:111], v[222:225], v[132:135], v[96:111]
	v_lshl_add_u64 v[172:173], v[172:173], 0, s[12:13]
	v_add_f32_e32 v242, v114, v242
	v_add_f32_e32 v243, v82, v243
	v_add_f32_e32 v242, v115, v242
	v_add_f32_e32 v243, v83, v243
	s_waitcnt lgkmcnt(8)
	v_mfma_f32_32x32x16_bf16 v[96:111], v[226:229], v[136:139], v[96:111]
	v_lshl_add_u64 v[174:175], v[174:175], 0, s[12:13]
	v_add_f32_e32 v242, v116, v242
	v_add_f32_e32 v243, v84, v243
	v_add_f32_e32 v242, v117, v242
	v_add_f32_e32 v243, v85, v243
	s_waitcnt lgkmcnt(7)
	v_mfma_f32_32x32x16_bf16 v[96:111], v[230:233], v[140:143], v[96:111]
	v_add_f32_e32 v242, v118, v242
	v_add_f32_e32 v243, v86, v243
	v_add_f32_e32 v242, v119, v242
	v_add_f32_e32 v243, v87, v243
	v_add_f32_e32 v242, v120, v242
	s_waitcnt lgkmcnt(6)
	v_mfma_f32_32x32x16_bf16 v[96:111], v[234:237], v[144:147], v[96:111]
	v_add_f32_e32 v243, v88, v243
	v_add_f32_e32 v242, v121, v242
	v_add_f32_e32 v243, v89, v243
	v_add_f32_e32 v242, v122, v242
	v_add_f32_e32 v243, v90, v243
	v_add_f32_e32 v242, v123, v242
	s_waitcnt lgkmcnt(5)
	v_mfma_f32_32x32x16_bf16 v[96:111], v[238:241], v[148:151], v[96:111]
	v_add_f32_e32 v243, v91, v243
	v_add_f32_e32 v242, v124, v242
	v_add_f32_e32 v243, v92, v243
	v_add_f32_e32 v242, v125, v242
	v_add_f32_e32 v243, v93, v243
	v_add_f32_e32 v242, v126, v242
	s_waitcnt lgkmcnt(4)
	v_mfma_f32_32x32x16_bf16 v[64:79], v[218:221], v[176:179], 0
	ds_read_b128 v[176:179], v193 offset:50176
	ds_read_b128 v[218:221], v188 offset:6656
	v_add_f32_e32 v243, v94, v243
	v_add_f32_e32 v242, v127, v242
	v_add_f32_e32 v243, v95, v243
	s_waitcnt lgkmcnt(5)
	v_mfma_f32_32x32x16_bf16 v[64:79], v[222:225], v[180:183], v[64:79]
	ds_read_b128 v[222:225], v188 offset:6688
	v_exp_f32_e32 v96, v96
	v_exp_f32_e32 v97, v97
	s_waitcnt lgkmcnt(5)
	v_mfma_f32_32x32x16_bf16 v[64:79], v[226:229], v[184:187], v[64:79]
	ds_read_b128 v[226:229], v188 offset:6720
	v_exp_f32_e32 v98, v98
	v_exp_f32_e32 v99, v99
	s_waitcnt lgkmcnt(5)
	v_mfma_f32_32x32x16_bf16 v[64:79], v[230:233], v[248:251], v[64:79]
	ds_read_b128 v[230:233], v188 offset:6752
	v_exp_f32_e32 v100, v100
	v_exp_f32_e32 v101, v101
	s_waitcnt lgkmcnt(5)
	v_mfma_f32_32x32x16_bf16 v[64:79], v[234:237], v[244:247], v[64:79]
	ds_read_b128 v[234:237], v188 offset:6784
	v_exp_f32_e32 v102, v102
	v_exp_f32_e32 v103, v103
	s_waitcnt lgkmcnt(5)
	v_mfma_f32_32x32x16_bf16 v[64:79], v[238:241], v[176:179], v[64:79]
	ds_read_b128 v[238:241], v188 offset:6816
	ds_read_b128 v[176:179], v193 offset:45056
	v_exp_f32_e32 v104, v104
	v_exp_f32_e32 v105, v105
	v_exp_f32_e32 v106, v106
	v_exp_f32_e32 v107, v107
	s_waitcnt lgkmcnt(6)
	v_mfma_f32_32x32x16_bf16 v[112:127], v[218:221], v[128:131], 0
	v_exp_f32_e32 v108, v108
	v_exp_f32_e32 v109, v109
	v_exp_f32_e32 v110, v110
	v_exp_f32_e32 v111, v111
	s_waitcnt lgkmcnt(5)
	v_mfma_f32_32x32x16_bf16 v[112:127], v[222:225], v[132:135], v[112:127]
	v_exp_f32_e32 v64, v64
	v_exp_f32_e32 v65, v65
	v_exp_f32_e32 v66, v66
	s_waitcnt lgkmcnt(4)
	v_mfma_f32_32x32x16_bf16 v[112:127], v[226:229], v[136:139], v[112:127]
	v_exp_f32_e32 v67, v67
	v_exp_f32_e32 v68, v68
	v_exp_f32_e32 v69, v69
	s_waitcnt lgkmcnt(3)
	v_mfma_f32_32x32x16_bf16 v[112:127], v[230:233], v[140:143], v[112:127]
	v_exp_f32_e32 v70, v70
	v_exp_f32_e32 v71, v71
	v_exp_f32_e32 v72, v72
	s_waitcnt lgkmcnt(2)
	v_mfma_f32_32x32x16_bf16 v[112:127], v[234:237], v[144:147], v[112:127]
	v_exp_f32_e32 v73, v73
	v_exp_f32_e32 v74, v74
	v_exp_f32_e32 v75, v75
	s_waitcnt lgkmcnt(1)
	v_mfma_f32_32x32x16_bf16 v[112:127], v[238:241], v[148:151], v[112:127]
	v_exp_f32_e32 v76, v76
	v_exp_f32_e32 v77, v77
	v_exp_f32_e32 v78, v78
	v_exp_f32_e32 v79, v79
	s_waitcnt lgkmcnt(0)
; #define ALAS __attribute__((address_space(3)))
; __device__ __forceinline__ s16x4 vtr(const ALAS unsigned char* p) { return __builtin_bit_cast(s16x4, __builtin_amdgcn_ds_read_tr16_b64_v4i16((ALAS s16x4*)p)); }
; #define AMFMA(a, b, c) __builtin_amdgcn_mfma_f32_32x32x16_bf16((a), (b), (c), 0, 0, 0)
; template <bool SUB> __device__ __forceinline__ void attn_unit_r2b(const AU& u, ALAS unsigned char* lds, float mb2) {
;     ...
;                 const bf16x8 k0 = *(const ALAS bf16x8*)(kb + d0 * 32), k1 = *(const ALAS bf16x8*)(kb + 32 * KP + d0 * 32); const bf16x8 qbv = *(const ALAS bf16x8*)(qbl + d0 * 1024);
;                 Sa0 = AMFMA(k0, qa[d0], Sa0); Sa1 = AMFMA(k1, qa[d0], Sa1); Sb0 = AMFMA(k0, qbv, Sb0); Sb1 = AMFMA(k1, qbv, Sb1);
;                 if (d0 & 1) __builtin_amdgcn_sched_barrier(0);
;             }
;     ...
;             R2B_SOFT(Sa0, Sa1, paa, la);
;             __builtin_amdgcn_sched_barrier(0);
;             R2B_SOFT(Sb0, Sb1, pab, lb);
;     ...
; #pragma unroll
;             for (int ks = 0; ks < 4; ++ks) {
;                 const s16x4 lo0 = vtr(vb + ks * 16 * VP), hi0 = vtr(vb + (ks * 16 + 8) * VP), lo1 = vtr(vb + ks * 16 * VP + 64), hi1 = vtr(vb + (ks * 16 + 8) * VP + 64);
;                 const bf16x8 vf0 = __builtin_shufflevector(lo0, hi0, 0, 1, 2, 3, 4, 5, 6, 7), vf1 = __builtin_shufflevector(lo1, hi1, 0, 1, 2, 3, 4, 5, 6, 7);
;                 oa0 = AMFMA(paa[ks], vf0, oa0); oa1 = AMFMA(paa[ks], vf1, oa1); ob0 = AMFMA(pab[ks], vf0, ob0); ob1 = AMFMA(pab[ks], vf1, ob1);
;             }
;         }
;         if (t + 1 < NT) { *(ALAS u32x4*)(lds + (cur ^ 1) * KBUF + kl0) = rk0; if (k2) *(ALAS u32x4*)(lds + (cur ^ 1) * KBUF + kl1) = rk1; *(ALAS u32x4*)(lds + (cur ^ 1) * VBUF + vl) = rv; }
	v_mfma_f32_32x32x16_bf16 v[80:95], v[218:221], v[176:179], 0
	ds_read_b128 v[176:179], v193 offset:50176
	v_cvt_pk_bf16_f32 v218, v96, v97
	v_cvt_pk_bf16_f32 v219, v98, v99
	v_cvt_pk_bf16_f32 v220, v100, v101
	v_cvt_pk_bf16_f32 v221, v102, v103
	v_mfma_f32_32x32x16_bf16 v[80:95], v[222:225], v[180:183], v[80:95]
	v_cvt_pk_bf16_f32 v222, v64, v65
	v_cvt_pk_bf16_f32 v223, v66, v67
	v_cvt_pk_bf16_f32 v224, v68, v69
	v_cvt_pk_bf16_f32 v225, v70, v71
	v_exp_f32_e32 v112, v112
	v_exp_f32_e32 v113, v113
	v_mfma_f32_32x32x16_bf16 v[80:95], v[226:229], v[184:187], v[80:95]
	v_cvt_pk_bf16_f32 v226, v104, v105
	v_cvt_pk_bf16_f32 v227, v106, v107
	v_cvt_pk_bf16_f32 v228, v108, v109
	v_cvt_pk_bf16_f32 v229, v110, v111
	v_exp_f32_e32 v114, v114
	v_exp_f32_e32 v115, v115
	ds_read_b64_tr_b16 v[184:185], v189 offset:26624
	ds_read_b64_tr_b16 v[186:187], v189 offset:27776
	v_mfma_f32_32x32x16_bf16 v[80:95], v[230:233], v[248:251], v[80:95]
	v_cvt_pk_bf16_f32 v230, v72, v73
	v_cvt_pk_bf16_f32 v231, v74, v75
	v_cvt_pk_bf16_f32 v232, v76, v77
	v_cvt_pk_bf16_f32 v233, v78, v79
	v_exp_f32_e32 v116, v116
	v_exp_f32_e32 v117, v117
	ds_read_b64_tr_b16 v[248:249], v189 offset:26688
	ds_read_b64_tr_b16 v[250:251], v189 offset:27840
	v_mfma_f32_32x32x16_bf16 v[80:95], v[234:237], v[244:247], v[80:95]
	v_exp_f32_e32 v118, v118
	v_exp_f32_e32 v119, v119
	v_exp_f32_e32 v120, v120
	v_exp_f32_e32 v121, v121
	ds_read_b64_tr_b16 v[244:245], v189 offset:28928
	ds_read_b64_tr_b16 v[246:247], v189 offset:30080
	s_waitcnt lgkmcnt(6)
	v_mfma_f32_32x32x16_bf16 v[80:95], v[238:241], v[176:179], v[80:95]
	v_exp_f32_e32 v122, v122
	v_exp_f32_e32 v123, v123
	v_exp_f32_e32 v124, v124
	v_exp_f32_e32 v125, v125
	s_waitcnt lgkmcnt(4)
	v_mfma_f32_32x32x16_bf16 v[32:47], v[218:221], v[184:187], v[32:47]
	v_exp_f32_e32 v126, v126
	v_exp_f32_e32 v127, v127
	v_cvt_pk_bf16_f32 v234, v112, v113
	v_cvt_pk_bf16_f32 v235, v114, v115
	v_cvt_pk_bf16_f32 v236, v116, v117
	v_cvt_pk_bf16_f32 v237, v118, v119
	s_waitcnt lgkmcnt(2)
	v_mfma_f32_32x32x16_bf16 v[48:63], v[218:221], v[248:251], v[48:63]
	v_exp_f32_e32 v80, v80
	v_exp_f32_e32 v81, v81
	v_exp_f32_e32 v82, v82
	v_exp_f32_e32 v83, v83
	v_mfma_f32_32x32x16_bf16 v[0:15], v[222:225], v[184:187], v[0:15]
	ds_read_b64_tr_b16 v[184:185], v189 offset:28992
	ds_read_b64_tr_b16 v[186:187], v189 offset:30144
	v_exp_f32_e32 v84, v84
	v_exp_f32_e32 v85, v85
	v_exp_f32_e32 v86, v86
	v_exp_f32_e32 v87, v87
	v_mfma_f32_32x32x16_bf16 v[16:31], v[222:225], v[248:251], v[16:31]
	ds_read_b64_tr_b16 v[248:249], v189 offset:31232
	ds_read_b64_tr_b16 v[250:251], v189 offset:32384
	v_exp_f32_e32 v88, v88
	v_exp_f32_e32 v89, v89
	v_exp_f32_e32 v90, v90
	v_exp_f32_e32 v91, v91
	s_waitcnt lgkmcnt(4)
	v_mfma_f32_32x32x16_bf16 v[32:47], v[226:229], v[244:247], v[32:47]
	v_exp_f32_e32 v92, v92
	v_exp_f32_e32 v93, v93
	v_exp_f32_e32 v94, v94
	v_exp_f32_e32 v95, v95
	s_waitcnt lgkmcnt(2)
	v_mfma_f32_32x32x16_bf16 v[48:63], v[226:229], v[184:187], v[48:63]
	v_cvt_pk_bf16_f32 v176, v120, v121
	v_cvt_pk_bf16_f32 v177, v122, v123
	v_cvt_pk_bf16_f32 v178, v124, v125
	v_cvt_pk_bf16_f32 v179, v126, v127
	v_cvt_pk_bf16_f32 v238, v80, v81
	v_cvt_pk_bf16_f32 v239, v82, v83
	v_cvt_pk_bf16_f32 v240, v84, v85
	v_cvt_pk_bf16_f32 v241, v86, v87
	v_mfma_f32_32x32x16_bf16 v[0:15], v[230:233], v[244:247], v[0:15]
	ds_read_b64_tr_b16 v[244:245], v189 offset:31296
	ds_read_b64_tr_b16 v[246:247], v189 offset:32448
	v_cvt_pk_bf16_f32 v180, v88, v89
	v_cvt_pk_bf16_f32 v181, v90, v91
	v_cvt_pk_bf16_f32 v182, v92, v93
	v_cvt_pk_bf16_f32 v183, v94, v95
	v_add_f32_e32 v164, v96, v164
	v_add_f32_e32 v165, v64, v165
	v_add_f32_e32 v164, v97, v164
	v_mfma_f32_32x32x16_bf16 v[16:31], v[230:233], v[184:187], v[16:31]
	ds_read_b64_tr_b16 v[184:185], v189 offset:33536
	ds_read_b64_tr_b16 v[186:187], v189 offset:34688
	v_add_f32_e32 v165, v65, v165
	v_add_f32_e32 v164, v98, v164
	v_add_f32_e32 v165, v66, v165
	v_add_f32_e32 v164, v99, v164
	v_add_f32_e32 v165, v67, v165
	s_waitcnt lgkmcnt(4)
	v_mfma_f32_32x32x16_bf16 v[32:47], v[234:237], v[248:251], v[32:47]
	v_add_f32_e32 v164, v100, v164
	v_add_f32_e32 v165, v68, v165
	v_add_f32_e32 v164, v101, v164
	v_add_f32_e32 v165, v69, v165
	v_add_f32_e32 v164, v102, v164
	v_add_f32_e32 v165, v70, v165
	s_waitcnt lgkmcnt(2)
	v_mfma_f32_32x32x16_bf16 v[48:63], v[234:237], v[244:247], v[48:63]
	v_add_f32_e32 v164, v103, v164
	v_add_f32_e32 v165, v71, v165
	v_add_f32_e32 v164, v104, v164
	v_add_f32_e32 v165, v72, v165
	v_add_f32_e32 v164, v105, v164
	v_add_f32_e32 v165, v73, v165
	v_mfma_f32_32x32x16_bf16 v[0:15], v[238:241], v[248:251], v[0:15]
	ds_read_b64_tr_b16 v[248:249], v189 offset:33600
	ds_read_b64_tr_b16 v[250:251], v189 offset:34752
	v_add_f32_e32 v164, v106, v164
	v_add_f32_e32 v165, v74, v165
	v_add_f32_e32 v164, v107, v164
	v_add_f32_e32 v165, v75, v165
	v_add_f32_e32 v164, v108, v164
	v_mfma_f32_32x32x16_bf16 v[16:31], v[238:241], v[244:247], v[16:31]
	v_add_f32_e32 v165, v76, v165
	v_add_f32_e32 v164, v109, v164
	v_add_f32_e32 v165, v77, v165
	v_add_f32_e32 v164, v110, v164
	v_add_f32_e32 v165, v78, v165
	v_add_f32_e32 v164, v111, v164
	s_waitcnt lgkmcnt(2)
	v_mfma_f32_32x32x16_bf16 v[32:47], v[176:179], v[184:187], v[32:47]
	v_add_f32_e32 v165, v79, v165
	s_andn2_b64 vcc, exec, s[56:57]
	s_waitcnt lgkmcnt(0)
	v_mfma_f32_32x32x16_bf16 v[48:63], v[176:179], v[248:251], v[48:63]
	s_cbranch_vccnz .Lr2b_nowrite
	s_xor_b32 s58, s58, 1
	s_mul_i32 s34, s58, 0x3400
	v_add_u32_e32 v217, s34, v194
	s_waitcnt vmcnt(0)
	ds_write_b128 v217, v[152:155]
	s_and_saveexec_b64 s[56:57], s[40:41]
	s_cbranch_execz .Lr2b_nok2w
	v_add_u32_e32 v217, s34, v195
	ds_write_b128 v217, v[156:159]
